# strategy 4b: static s_setprio 1 for waves 4-7 over the non-GEMM phases P2..F only; GEMM flips kept
# baseline (speedup 1.0000x reference)
;     __device__ __forceinline__ bf16_t* bfp(size_t off) const { return (bf16_t*)(ws + off); }
; #define FRESH() do { int _t = threadIdx.x; asm volatile("" : "+v"(_t)); C.tid = _t; C.lane = _t & 63; C.wave = __builtin_amdgcn_readfirstlane(_t >> 6); size_t _z = 0; asm volatile("" : "+s"(_z)); C.ws = prm.ws + _z; C.out = prm.out + _z; } while (0)
; #define GSYNC() do { xcd_barrier(xbar); FRESH(); } while (0)
; __device__ __forceinline__ void attn_fetch(const Ctx& C, int it, u32x4 (&kv)[4], u32x4 (&vv)[4], u32x4 (&qv)[2]) {
;     ...
;     const int b = it / 384, rem = it % 384, hq = rem >> 5, kk = rem & 31, g = hq >> 2, dil = 1 << (2 * g), n = SEQ / dil, nblk = 32 / dil, r = kk / nblk, jb = kk % nblk;
;     const bf16_t* pd = C.bfp(OFF_PROJD);
; #pragma unroll
;     for (int k = 0; k < 4; ++k) { const int id = tid + NTHR * k, cidx = id >> 3, ch = id & 7, ik = 128 * jb - 64 + cidx;
;         kv[k] = (u32x4){0u, 0u, 0u, 0u}; vv[k] = (u32x4){0u, 0u, 0u, 0u};
;         if (ik >= 0 && ik < n) { const bf16_t* row = pd + (size_t)(b * SEQ + r + dil * ik) * 2304; kv[k] = *(const u32x4*)(row + 768 + hq * 64 + ch * 8); vv[k] = *(const u32x4*)(row + 1536 + hq * 64 + ch * 8); } }
; __global__ void __launch_bounds__(NTHR, 2) fwd_megakernel(Params prm) {
;     ...
;         GSYNC();
;         FRESH();
;         { u32x4 akv[4], avv[4], aqv[2]; attn_fetch(C, bid, akv, avv, aqv);
.LBB0_334:
	s_or_b64 exec, exec, s[0:1]
	s_waitcnt lgkmcnt(0)
	v_mov_b32_e32 v0, v224
	s_mov_b64 s[0:1], 0
	s_barrier
	v_readfirstlane_b32 s4, v224
	s_nop 3
	s_lshr_b32 s4, s4, 6
	s_cmp_lt_u32 s4, 4
	s_cbranch_scc1 .Lmy_prio_p2
	s_setprio 1
.Lmy_prio_p2:
	v_mov_b32_e32 v40, v224
	s_mov_b64 s[0:1], 0
	s_add_u32 s36, s24, s0
	v_lshlrev_b32_e32 v41, 3, v40
	v_ashrrev_i32_e32 v92, 3, v40
	v_readlane_b32 s0, v253, 22
	s_addc_u32 s40, s25, s1
	v_and_b32_e32 v4, 56, v41
	v_add_u32_e32 v12, s0, v92
	v_readlane_b32 s0, v253, 20
	v_mov_b32_e32 v2, v65
	v_mov_b32_e32 v3, v65
	s_add_u32 s42, s36, 0xe000000
	v_cmp_lt_i32_e32 vcc, -1, v12
	v_cmp_gt_i32_e64 s[4:5], s0, v12
	v_mov_b32_e32 v0, v65
	v_mov_b32_e32 v1, v65
	v_lshlrev_b32_e32 v78, 1, v4
	v_mov_b64_e32 v[10:11], v[2:3]
	v_mov_b64_e32 v[6:7], v[2:3]
	v_readfirstlane_b32 s6, v40
	s_addc_u32 s43, s40, 0
	s_and_b64 s[4:5], vcc, s[4:5]
	v_mov_b64_e32 v[8:9], v[0:1]
	v_mov_b64_e32 v[4:5], v[0:1]
	s_and_saveexec_b64 s[0:1], s[4:5]
	s_cbranch_execz .LBB0_336
	v_readlane_b32 s4, v253, 19
	v_mov_b32_e32 v79, v65
	s_nop 0
	v_lshlrev_b32_e32 v4, s4, v12
	v_readlane_b32 s4, v253, 16
	s_nop 1
	v_add_u32_e32 v6, s4, v4
	v_mov_b64_e32 v[4:5], s[42:43]
	v_mad_i64_i32 v[4:5], s[4:5], v6, s92, v[4:5]
	v_readlane_b32 s4, v253, 17
	v_readlane_b32 s5, v253, 18
	s_nop 1
	v_lshl_add_u64 v[4:5], s[4:5], 1, v[4:5]
	v_lshl_add_u64 v[8:9], v[4:5], 0, v[78:79]
	global_load_dwordx4 v[4:7], v[8:9], off offset:1536
	s_nop 0
	global_load_dwordx4 v[8:11], v[8:9], off offset:3072
